# layer-0 w_up/w_down conversion tiles moved from beside the scan into the output projection's partial last round; on top of pipelined conv + prep_item prefetch
# baseline (speedup 1.0000x reference)
; __device__ void phase_mixer(const Params& p, int l, LAS unsigned char* lds) {
;     ...
;     if (G > 128) {
;         if (bid < 128) scan_chain(p, l, (bid >> 4) * 8 + (bid & 7), (bid >> 3) & 1, lds);
;         else { for (int t = bid - 128; t < (ntile < SGU_IN_M2 ? ntile : SGU_IN_M2); t += G - 128) sgu_tile(p, l, t, lds);
;                if (l == 0) for (int t = NT_EARLY + bid - 128; t < NT_LAYER; t += G - 128) transpose_tile(p, lds, 0, t); }
.LBB0_379:
	v_readlane_b32 s0, v242, 3
	v_readlane_b32 s6, v240, 28
	v_readlane_b32 s1, v242, 4
	v_readlane_b32 s7, v240, 29
	s_and_b64 s[0:1], s[6:7], s[0:1]
	s_andn2_b64 vcc, exec, s[0:1]
	v_readlane_b32 s5, v242, 5
	s_movk_i32 s11, 0x104
	s_movk_i32 s12, 0xb00
	s_cmp_eq_u32 s46, 0x100
	s_cbranch_scc1 .LBB0_381
	s_cbranch_vccnz .LBB0_381

; #define LAS __attribute__((address_space(3)))
; __device__ __forceinline__ unsigned pk_bf16(float a, float b) { f32x2 v = {a, b}; bf2_t r = __builtin_convertvector(v, bf2_t); return __builtin_bit_cast(unsigned, r); }
; __device__ __forceinline__ int opaque_tid() { int t = threadIdx.x; asm volatile("" : "+v"(t)); return t; }
; __device__ void transpose_tile(const Params& p, LAS unsigned char* lds, int l, int r) {
;     const int tid = opaque_tid();
;     const float* src; bf16_t* dst; int K, N;
;     if (r < 896) { src = p.in[8] + (size_t)l * D * PW; dst = (bf16_t*)(p.ws + WS_WIN) + (size_t)l * PW * D; K = D; N = PW; }
;     else if (r < 1152) { r -= 896; src = p.in[16] + (size_t)l * D * D; dst = (bf16_t*)(p.ws + WS_WOUT) + (size_t)l * D * D; K = D; N = D; }
;     else if (r < 2560) { r -= 1152; src = p.in[17] + (size_t)l * D * UPW; dst = (bf16_t*)(p.ws + WS_WUP) + (size_t)l * UPW * D; K = D; N = UPW; }
;     else { r -= 2560; src = p.in[20] + (size_t)l * FF * D; dst = (bf16_t*)(p.ws + WS_WDOWN) + (size_t)l * D * FF; K = FF; N = D; }
;     const int ntn = N >> 6, kt = r / ntn, nt = r % ntn;
;     LAS float* tile = (LAS float*)lds;
;     { const int kk = tid >> 3, n8 = (tid & 7) * 8; const float* sp = src + (size_t)(kt * 64 + kk) * N + nt * 64 + n8;
;       const f32x4 a = *(const f32x4*)sp, b = *(const f32x4*)(sp + 4);
;       LAS float* tp = tile + kk * 65 + n8; tp[0] = a[0]; tp[1] = a[1]; tp[2] = a[2]; tp[3] = a[3]; tp[4] = b[0]; tp[5] = b[1]; tp[6] = b[2]; tp[7] = b[3]; }
;     __syncthreads();
;     { const int nn = tid >> 3, k8 = (tid & 7) * 8; float v[8];
; #pragma unroll
;       for (int i = 0; i < 8; ++i) v[i] = tile[(k8 + i) * 65 + nn];
;       u32x4 w; w.x = pk_bf16(v[0], v[1]); w.y = pk_bf16(v[2], v[3]); w.z = pk_bf16(v[4], v[5]); w.w = pk_bf16(v[6], v[7]);
;       *(u32x4*)(dst + (size_t)(nt * 64 + nn) * K + kt * 64 + k8) = w; }
;     __syncthreads();
; __global__ void __launch_bounds__(512, 2) fwd_megakernel(Params p) {
;     ...
;             const int nwg = (Mfull / 256) * (D / 256), full = (nwg / G) * G, busy = nwg - full;
;             if (busy > 0 && busy < G) { if (bid >= busy) for (int t = bid - busy; t < NT_LAYER; t += G - busy) transpose_tile(p, lds, l + 1, t); }
;             else for (int t = bid; t < NT_LAYER; t += G) transpose_tile(p, lds, l + 1, t);
.LBB0_520:
	v_readlane_b32 s0, v240, 28
	v_readlane_b32 s1, v240, 29
	s_cmp_lg_u32 s46, 0x100
	s_cbranch_scc1 .Ltr2_done
	s_and_b64 vcc, exec, s[0:1]
	s_cbranch_vccz .Ltr2_done
	s_cmp_lt_u32 s92, 32
	s_cbranch_scc1 .Ltr2_done
	s_add_i32 s22, s92, 0x460
	s_movk_i32 s98, 0x104
	s_movk_i32 s99, 0xb00
	s_mov_b32 s21, 0
.Ltr2_loop:
	s_cmpk_lt_u32 s22, 0xa00
	s_movk_i32 s0, 0xf600
	s_cselect_b32 s0, 0xfffffb80, s0
	s_mov_b32 s6, 0x1200000
	s_cselect_b32 s20, s81, 0x400
	s_cselect_b32 s1, 0x400, s99
	s_cselect_b32 s6, s6, 0x2800000
	s_cselect_b32 s7, s51, s57
	s_cselect_b32 s8, s50, s56
	s_add_i32 s0, s0, s22
	s_add_u32 s38, s62, s6
	s_addc_u32 s39, s63, 0
	s_lshr_b32 s6, s20, 6
	v_cvt_f32_u32_e32 v3, s6
	v_mov_b32_e32 v0, s8
	v_mov_b32_e32 v1, s7
	s_sub_i32 s7, 0, s6
	v_rcp_iflag_f32_e32 v3, v3
	v_mov_b32_e32 v2, v135
	v_mul_f32_e32 v3, 0x4f7ffffe, v3
	v_cvt_u32_f32_e32 v3, v3
	v_ashrrev_i32_e32 v5, 3, v2
	v_lshlrev_b32_e32 v2, 3, v2
	v_and_b32_e32 v4, 56, v2
	v_readfirstlane_b32 s8, v3
	s_mul_i32 s7, s7, s8
	s_mul_hi_u32 s7, s8, s7
	s_add_i32 s8, s8, s7
	s_mul_hi_u32 s7, s0, s8
	s_mul_i32 s8, s7, s6
	s_sub_i32 s8, s0, s8
	s_add_i32 s9, s7, 1
	s_sub_i32 s10, s8, s6
	s_cmp_ge_u32 s8, s6
	s_cselect_b32 s7, s9, s7
	s_cselect_b32 s8, s10, s8
	s_add_i32 s9, s7, 1
	s_cmp_ge_u32 s8, s6
	s_cselect_b32 s7, s9, s7
	s_mul_i32 s6, s7, s6
	s_sub_i32 s8, s0, s6
	s_lshl_b32 s0, s7, 6
	v_add_u32_e32 v2, s0, v5
	v_mad_i64_i32 v[2:3], s[6:7], v2, s20, 0
	v_lshl_add_u64 v[0:1], v[2:3], 2, v[0:1]
	s_lshl_b32 s20, s8, 6
	v_lshl_add_u64 v[2:3], s[20:21], 2, v[0:1]
	v_lshlrev_b32_e32 v0, 2, v4
	v_mov_b32_e32 v1, v8
	v_lshl_add_u64 v[2:3], v[2:3], 0, v[0:1]
	global_load_dwordx4 v[10:13], v[2:3], off offset:16
	global_load_dwordx4 v[14:17], v[2:3], off
	v_mul_lo_u32 v1, v5, s98
	v_add_u32_e32 v1, 16, v1
	v_add_u32_e32 v0, v1, v0
	s_add_i32 s22, s22, 0xe0
	s_cmpk_gt_i32 s22, 0xcbf
	s_waitcnt vmcnt(0)
	ds_write2_b32 v0, v14, v15 offset1:1
	ds_write2_b32 v0, v16, v17 offset0:2 offset1:3
	ds_write2_b32 v0, v10, v11 offset0:4 offset1:5
	ds_write2_b32 v0, v12, v13 offset0:6 offset1:7
	v_lshlrev_b32_e32 v0, 8, v5
	v_sub_u32_e32 v0, v1, v0
	v_mad_u32_u24 v6, v4, s98, v0
	s_waitcnt lgkmcnt(0)
	s_barrier
	ds_read2_b32 v[0:1], v6 offset1:65
	ds_read2_b32 v[2:3], v6 offset0:130 offset1:195
	v_add_u32_e32 v9, 0x400, v6
	ds_read2_b32 v[6:7], v9 offset0:4 offset1:69
	ds_read2_b32 v[10:11], v9 offset0:134 offset1:199
	v_add_u32_e32 v5, s20, v5
	s_waitcnt lgkmcnt(3)
	v_cvt_pk_bf16_f32 v0, v0, v1
	s_waitcnt lgkmcnt(2)
	v_cvt_pk_bf16_f32 v1, v2, v3
	s_waitcnt lgkmcnt(1)
	v_cvt_pk_bf16_f32 v2, v6, v7
	v_mad_i64_i32 v[6:7], s[6:7], s1, v5, 0
	v_lshl_add_u64 v[6:7], v[6:7], 1, s[38:39]
	s_mov_b32 s1, s3
	v_lshl_add_u64 v[6:7], s[0:1], 1, v[6:7]
	v_lshlrev_b32_e32 v4, 1, v4
	v_mov_b32_e32 v5, v8
	s_waitcnt lgkmcnt(0)
	v_cvt_pk_bf16_f32 v3, v10, v11
	v_lshl_add_u64 v[4:5], v[6:7], 0, v[4:5]
	global_store_dwordx4 v[4:5], v[0:3], off
	s_barrier
	s_cbranch_scc0 .Ltr2_loop
